# fused P6: residual rows touched one BODY before the epilogue (scratch loads) so the epilogue's loads do not form an HBM burst with idle matrix cores
# baseline (speedup 1.0000x reference)
.LBB0_883:
	s_add_u32 s42, s20, 0x100
	s_addc_u32 s43, s21, 0
	s_cmpk_eq_i32 s89, 0x7c
	s_cselect_b32 s28, s86, s42
	s_cselect_b32 s29, s81, s43
	s_cselect_b32 s23, s37, s88
	s_cselect_b32 s22, s87, vcc_lo
	s_add_u32 s26, s28, 0x80
	s_addc_u32 s27, s29, 0
	s_add_u32 s66, s22, 0x80
	s_addc_u32 s67, s23, 0
	s_add_u32 s90, s20, 0x200080
	s_addc_u32 s91, s21, 0
	s_add_u32 s52, s28, 0x200000
	s_addc_u32 s53, s29, 0
	s_add_u32 s56, s22, 0x200000
	s_addc_u32 s57, s23, 0
	s_add_u32 s20, s22, 0x200080
	s_addc_u32 s21, s23, 0
	s_add_i32 s92, 0, 0x10000
	s_add_i32 s93, 0, 0x14000
	v_add_u32_e32 v140, s92, v203
	v_add_u32_e32 v156, s93, v203
	ds_read_b128 v[128:131], v140
	ds_read_b128 v[132:135], v140 offset:1024
	ds_read_b128 v[136:139], v140 offset:2048
	ds_read_b128 v[140:143], v140 offset:3072
	ds_read_b128 v[144:147], v156
	ds_read_b128 v[148:151], v156 offset:1024
	ds_read_b128 v[152:155], v156 offset:2048
	ds_read_b128 v[156:159], v156 offset:3072
	s_add_i32 m0, s73, 0xc000
	ds_read_b128 v[160:163], v205
	ds_read_b128 v[164:167], v205 offset:1024
	ds_read_b128 v[168:171], v205 offset:2048
	ds_read_b128 v[172:175], v205 offset:3072
	ds_read_b128 v[176:179], v205 offset:4096
	ds_read_b128 v[180:183], v205 offset:5120
	ds_read_b128 v[184:187], v205 offset:6144
	ds_read_b128 v[188:191], v205 offset:7168
	global_load_lds_dwordx4 v202, s[90:91]
	s_add_i32 m0, s73, 0xe000
	s_nop 0
	global_load_lds_dwordx4 v204, s[90:91]
	s_waitcnt vmcnt(8)
	s_waitcnt lgkmcnt(0)
	s_barrier
	s_setprio 1
	s_waitcnt lgkmcnt(0)
	v_mfma_f32_16x16x32_bf16 v[124:127], v[128:131], v[160:163], v[124:127]
	v_mfma_f32_16x16x32_bf16 v[120:123], v[136:139], v[160:163], v[120:123]
	v_mfma_f32_16x16x32_bf16 v[108:111], v[128:131], v[168:171], v[108:111]
	v_mfma_f32_16x16x32_bf16 v[104:107], v[136:139], v[168:171], v[104:107]
	v_mfma_f32_16x16x32_bf16 v[92:95], v[128:131], v[176:179], v[92:95]
	v_mfma_f32_16x16x32_bf16 v[88:91], v[136:139], v[176:179], v[88:91]
	v_mfma_f32_16x16x32_bf16 v[76:79], v[128:131], v[184:187], v[76:79]
	v_mfma_f32_16x16x32_bf16 v[72:75], v[136:139], v[184:187], v[72:75]
	v_mfma_f32_16x16x32_bf16 v[124:127], v[132:135], v[164:167], v[124:127]
	v_mfma_f32_16x16x32_bf16 v[120:123], v[140:143], v[164:167], v[120:123]
	v_mfma_f32_16x16x32_bf16 v[108:111], v[132:135], v[172:175], v[108:111]
	v_mfma_f32_16x16x32_bf16 v[104:107], v[140:143], v[172:175], v[104:107]
	v_mfma_f32_16x16x32_bf16 v[92:95], v[132:135], v[180:183], v[92:95]
	v_mfma_f32_16x16x32_bf16 v[88:91], v[140:143], v[180:183], v[88:91]
	v_mfma_f32_16x16x32_bf16 v[76:79], v[132:135], v[188:191], v[76:79]
	v_mfma_f32_16x16x32_bf16 v[72:75], v[140:143], v[188:191], v[72:75]
	s_setprio 0
	s_setprio 1
	v_mfma_f32_16x16x32_bf16 v[116:119], v[144:147], v[160:163], v[116:119]
	v_mfma_f32_16x16x32_bf16 v[112:115], v[152:155], v[160:163], v[112:115]
	v_mfma_f32_16x16x32_bf16 v[100:103], v[144:147], v[168:171], v[100:103]
	v_mfma_f32_16x16x32_bf16 v[96:99], v[152:155], v[168:171], v[96:99]
	v_mfma_f32_16x16x32_bf16 v[84:87], v[144:147], v[176:179], v[84:87]
	v_mfma_f32_16x16x32_bf16 v[80:83], v[152:155], v[176:179], v[80:83]
	v_mfma_f32_16x16x32_bf16 v[68:71], v[144:147], v[184:187], v[68:71]
	v_mfma_f32_16x16x32_bf16 v[64:67], v[152:155], v[184:187], v[64:67]
	v_mfma_f32_16x16x32_bf16 v[116:119], v[148:151], v[164:167], v[116:119]
	v_mfma_f32_16x16x32_bf16 v[112:115], v[156:159], v[164:167], v[112:115]
	v_mfma_f32_16x16x32_bf16 v[100:103], v[148:151], v[172:175], v[100:103]
	v_mfma_f32_16x16x32_bf16 v[96:99], v[156:159], v[172:175], v[96:99]
	v_mfma_f32_16x16x32_bf16 v[84:87], v[148:151], v[180:183], v[84:87]
	v_mfma_f32_16x16x32_bf16 v[80:83], v[156:159], v[180:183], v[80:83]
	v_mfma_f32_16x16x32_bf16 v[68:71], v[148:151], v[188:191], v[68:71]
	v_mfma_f32_16x16x32_bf16 v[64:67], v[156:159], v[188:191], v[64:67]
	s_setprio 0
	s_barrier
	s_add_i32 s90, s92, s33
	s_mov_b32 m0, s90
	ds_read_b128 v[160:163], v205 offset:16384
	ds_read_b128 v[164:167], v205 offset:17408
	ds_read_b128 v[168:171], v205 offset:18432
	ds_read_b128 v[172:175], v205 offset:19456
	ds_read_b128 v[176:179], v205 offset:20480
	ds_read_b128 v[180:183], v205 offset:21504
	ds_read_b128 v[184:187], v205 offset:22528
	ds_read_b128 v[188:191], v205 offset:23552
	global_load_lds_dwordx4 v192, s[22:23]
	s_add_i32 m0, s90, 0x2000
	s_nop 0
	global_load_lds_dwordx4 v206, s[22:23]
	s_add_i32 s22, s93, s33
	s_mov_b32 m0, s22
	s_nop 0
	global_load_lds_dwordx4 v192, s[56:57]
	s_add_i32 m0, s22, 0x2000
	s_nop 0
	global_load_lds_dwordx4 v206, s[56:57]
	s_mov_b32 m0, s73
	s_nop 0
	global_load_lds_dwordx4 v202, s[28:29]
	s_mov_b32 m0, s34
	s_nop 0
	global_load_lds_dwordx4 v204, s[28:29]
	s_waitcnt vmcnt(8)
	s_waitcnt lgkmcnt(0)
	s_barrier
	s_setprio 1
	s_waitcnt lgkmcnt(0)
	v_mfma_f32_16x16x32_bf16 v[60:63], v[128:131], v[160:163], v[60:63]
	v_mfma_f32_16x16x32_bf16 v[56:59], v[136:139], v[160:163], v[56:59]
	v_mfma_f32_16x16x32_bf16 v[44:47], v[128:131], v[168:171], v[44:47]
	v_mfma_f32_16x16x32_bf16 v[40:43], v[136:139], v[168:171], v[40:43]
	v_mfma_f32_16x16x32_bf16 v[28:31], v[128:131], v[176:179], v[28:31]
	v_mfma_f32_16x16x32_bf16 v[24:27], v[136:139], v[176:179], v[24:27]
	v_mfma_f32_16x16x32_bf16 v[12:15], v[128:131], v[184:187], v[12:15]
	v_mfma_f32_16x16x32_bf16 v[8:11], v[136:139], v[184:187], v[8:11]
	v_mfma_f32_16x16x32_bf16 v[60:63], v[132:135], v[164:167], v[60:63]
	v_mfma_f32_16x16x32_bf16 v[56:59], v[140:143], v[164:167], v[56:59]
	v_mfma_f32_16x16x32_bf16 v[44:47], v[132:135], v[172:175], v[44:47]
	v_mfma_f32_16x16x32_bf16 v[40:43], v[140:143], v[172:175], v[40:43]
	v_mfma_f32_16x16x32_bf16 v[28:31], v[132:135], v[180:183], v[28:31]
	v_mfma_f32_16x16x32_bf16 v[24:27], v[140:143], v[180:183], v[24:27]
	v_mfma_f32_16x16x32_bf16 v[12:15], v[132:135], v[188:191], v[12:15]
	v_mfma_f32_16x16x32_bf16 v[8:11], v[140:143], v[188:191], v[8:11]
	s_setprio 0
	s_setprio 1
	v_mfma_f32_16x16x32_bf16 v[52:55], v[144:147], v[160:163], v[52:55]
	v_mfma_f32_16x16x32_bf16 v[48:51], v[152:155], v[160:163], v[48:51]
	v_mfma_f32_16x16x32_bf16 v[36:39], v[144:147], v[168:171], v[36:39]
	v_mfma_f32_16x16x32_bf16 v[32:35], v[152:155], v[168:171], v[32:35]
	v_mfma_f32_16x16x32_bf16 v[20:23], v[144:147], v[176:179], v[20:23]
	v_mfma_f32_16x16x32_bf16 v[16:19], v[152:155], v[176:179], v[16:19]
	v_mfma_f32_16x16x32_bf16 v[4:7], v[144:147], v[184:187], v[4:7]
	v_mfma_f32_16x16x32_bf16 v[0:3], v[152:155], v[184:187], v[0:3]
	v_mfma_f32_16x16x32_bf16 v[52:55], v[148:151], v[164:167], v[52:55]
	v_mfma_f32_16x16x32_bf16 v[48:51], v[156:159], v[164:167], v[48:51]
	v_mfma_f32_16x16x32_bf16 v[36:39], v[148:151], v[172:175], v[36:39]
	v_mfma_f32_16x16x32_bf16 v[32:35], v[156:159], v[172:175], v[32:35]
	v_mfma_f32_16x16x32_bf16 v[20:23], v[148:151], v[180:183], v[20:23]
	v_mfma_f32_16x16x32_bf16 v[16:19], v[156:159], v[180:183], v[16:19]
	v_mfma_f32_16x16x32_bf16 v[4:7], v[148:151], v[188:191], v[4:7]
	v_mfma_f32_16x16x32_bf16 v[0:3], v[156:159], v[188:191], v[0:3]
	s_setprio 0
	s_barrier
	s_add_i32 s22, 0, 0x18000
	s_add_i32 s23, 0, 0x1c000
	v_add_u32_e32 v140, s22, v203
	v_add_u32_e32 v156, s23, v203
	ds_read_b128 v[128:131], v140
	ds_read_b128 v[132:135], v140 offset:1024
	ds_read_b128 v[136:139], v140 offset:2048
	ds_read_b128 v[140:143], v140 offset:3072
	ds_read_b128 v[144:147], v156
	ds_read_b128 v[148:151], v156 offset:1024
	ds_read_b128 v[152:155], v156 offset:2048
	ds_read_b128 v[156:159], v156 offset:3072
	s_mov_b32 m0, s35
	ds_read_b128 v[160:163], v205 offset:32768
	ds_read_b128 v[164:167], v205 offset:33792
	ds_read_b128 v[168:171], v205 offset:34816
	ds_read_b128 v[172:175], v205 offset:35840
	ds_read_b128 v[176:179], v205 offset:36864
	ds_read_b128 v[180:183], v205 offset:37888
	ds_read_b128 v[184:187], v205 offset:38912
	ds_read_b128 v[188:191], v205 offset:39936
	global_load_lds_dwordx4 v202, s[52:53]
	s_mov_b32 m0, s0
	s_nop 0
	global_load_lds_dwordx4 v204, s[52:53]
	s_waitcnt vmcnt(8)
	s_waitcnt lgkmcnt(0)
	s_barrier
	s_setprio 1
	s_waitcnt lgkmcnt(0)
	v_mfma_f32_16x16x32_bf16 v[124:127], v[128:131], v[160:163], v[124:127]
	v_mfma_f32_16x16x32_bf16 v[120:123], v[136:139], v[160:163], v[120:123]
	v_mfma_f32_16x16x32_bf16 v[108:111], v[128:131], v[168:171], v[108:111]
	v_mfma_f32_16x16x32_bf16 v[104:107], v[136:139], v[168:171], v[104:107]
	v_mfma_f32_16x16x32_bf16 v[92:95], v[128:131], v[176:179], v[92:95]
	v_mfma_f32_16x16x32_bf16 v[88:91], v[136:139], v[176:179], v[88:91]
	v_mfma_f32_16x16x32_bf16 v[76:79], v[128:131], v[184:187], v[76:79]
	v_mfma_f32_16x16x32_bf16 v[72:75], v[136:139], v[184:187], v[72:75]
	v_mfma_f32_16x16x32_bf16 v[124:127], v[132:135], v[164:167], v[124:127]
	v_mfma_f32_16x16x32_bf16 v[120:123], v[140:143], v[164:167], v[120:123]
	v_mfma_f32_16x16x32_bf16 v[108:111], v[132:135], v[172:175], v[108:111]
	v_mfma_f32_16x16x32_bf16 v[104:107], v[140:143], v[172:175], v[104:107]
	v_mfma_f32_16x16x32_bf16 v[92:95], v[132:135], v[180:183], v[92:95]
	v_mfma_f32_16x16x32_bf16 v[88:91], v[140:143], v[180:183], v[88:91]
	v_mfma_f32_16x16x32_bf16 v[76:79], v[132:135], v[188:191], v[76:79]
	v_mfma_f32_16x16x32_bf16 v[72:75], v[140:143], v[188:191], v[72:75]
	s_setprio 0
	s_setprio 1
	v_mfma_f32_16x16x32_bf16 v[116:119], v[144:147], v[160:163], v[116:119]
	v_mfma_f32_16x16x32_bf16 v[112:115], v[152:155], v[160:163], v[112:115]
	v_mfma_f32_16x16x32_bf16 v[100:103], v[144:147], v[168:171], v[100:103]
	v_mfma_f32_16x16x32_bf16 v[96:99], v[152:155], v[168:171], v[96:99]
	v_mfma_f32_16x16x32_bf16 v[84:87], v[144:147], v[176:179], v[84:87]
	v_mfma_f32_16x16x32_bf16 v[80:83], v[152:155], v[176:179], v[80:83]
	v_mfma_f32_16x16x32_bf16 v[68:71], v[144:147], v[184:187], v[68:71]
	v_mfma_f32_16x16x32_bf16 v[64:67], v[152:155], v[184:187], v[64:67]
	v_mfma_f32_16x16x32_bf16 v[116:119], v[148:151], v[164:167], v[116:119]
	v_mfma_f32_16x16x32_bf16 v[112:115], v[156:159], v[164:167], v[112:115]
	v_mfma_f32_16x16x32_bf16 v[100:103], v[148:151], v[172:175], v[100:103]
	v_mfma_f32_16x16x32_bf16 v[96:99], v[156:159], v[172:175], v[96:99]
	v_mfma_f32_16x16x32_bf16 v[84:87], v[148:151], v[180:183], v[84:87]
	v_mfma_f32_16x16x32_bf16 v[80:83], v[156:159], v[180:183], v[80:83]
	v_mfma_f32_16x16x32_bf16 v[68:71], v[148:151], v[188:191], v[68:71]
	v_mfma_f32_16x16x32_bf16 v[64:67], v[156:159], v[188:191], v[64:67]
	s_setprio 0
	s_barrier
; #define PG8_MMA(ai, bj, At, Bt) do { __builtin_amdgcn_s_setprio(1); _Pragma("unroll") for (int m = 0; m < 4; ++m) _Pragma("unroll") for (int n = 0; n < 2; ++n) _Pragma("unroll") for (int k = 0; k < 2; ++k) \
;         acc[ai][bj][m][n] = __builtin_amdgcn_mfma_f32_16x16x32_bf16(Bt[n][k], At[m][k], acc[ai][bj][m][n], 0, 0, 0); __builtin_amdgcn_s_setprio(0); } while (0)
;     __device__ __forceinline__ void operator()(f32x4 (&acc)[2][2][4][2], const Unit& u, int wr, int wc, int fr, int fq) const {
;     ...
;             for (int ai = 0; ai < 2; ++ai)
; #pragma unroll
;                 for (int m = 0; m < 4; ++m) { const size_t off = (size_t)(row0 + ai * HALF + m * 16) * ldc + col0;
; #pragma unroll
;                     for (int bj = 0; bj < 2; ++bj) bv[ai][m][bj] = __builtin_nontemporal_load((const u32x4*)(hb + off + bj * HALF)); }
;     ...
;         { const int tmid = (TSW > 0 && TSW < nt) ? TSW : nt;
;           _Pragma("unroll 1") for (int t = 0; t < tmid; t += 2) { PG8_BODY(PG8_MMA) }
	s_add_i32 s22, s22, s33
	s_mov_b32 m0, s22
	ds_read_b128 v[160:163], v205 offset:49152
	ds_read_b128 v[164:167], v205 offset:50176
	ds_read_b128 v[168:171], v205 offset:51200
	ds_read_b128 v[172:175], v205 offset:52224
	ds_read_b128 v[176:179], v205 offset:53248
	ds_read_b128 v[180:183], v205 offset:54272
	ds_read_b128 v[184:187], v205 offset:55296
	ds_read_b128 v[188:191], v205 offset:56320
	global_load_lds_dwordx4 v192, s[66:67]
	s_add_i32 m0, s22, 0x2000
	s_add_i32 s22, s23, s33
	global_load_lds_dwordx4 v206, s[66:67]
	s_mov_b32 m0, s22
	s_nop 0
	global_load_lds_dwordx4 v192, s[20:21]
	s_add_i32 m0, s22, 0x2000
	s_nop 0
	global_load_lds_dwordx4 v206, s[20:21]
	s_mov_b32 m0, s1
	s_nop 0
	global_load_lds_dwordx4 v202, s[26:27]
	s_mov_b32 m0, s54
	s_nop 0
	global_load_lds_dwordx4 v204, s[26:27]
	s_waitcnt vmcnt(8)
	s_waitcnt lgkmcnt(0)
	s_barrier
	s_setprio 1
	s_waitcnt lgkmcnt(0)
	v_mfma_f32_16x16x32_bf16 v[60:63], v[128:131], v[160:163], v[60:63]
	v_mfma_f32_16x16x32_bf16 v[56:59], v[136:139], v[160:163], v[56:59]
	v_mfma_f32_16x16x32_bf16 v[44:47], v[128:131], v[168:171], v[44:47]
	v_mfma_f32_16x16x32_bf16 v[40:43], v[136:139], v[168:171], v[40:43]
	v_mfma_f32_16x16x32_bf16 v[28:31], v[128:131], v[176:179], v[28:31]
	v_mfma_f32_16x16x32_bf16 v[24:27], v[136:139], v[176:179], v[24:27]
	v_mfma_f32_16x16x32_bf16 v[12:15], v[128:131], v[184:187], v[12:15]
	v_mfma_f32_16x16x32_bf16 v[8:11], v[136:139], v[184:187], v[8:11]
	v_mfma_f32_16x16x32_bf16 v[60:63], v[132:135], v[164:167], v[60:63]
	v_mfma_f32_16x16x32_bf16 v[56:59], v[140:143], v[164:167], v[56:59]
	v_mfma_f32_16x16x32_bf16 v[44:47], v[132:135], v[172:175], v[44:47]
	v_mfma_f32_16x16x32_bf16 v[40:43], v[140:143], v[172:175], v[40:43]
	v_mfma_f32_16x16x32_bf16 v[28:31], v[132:135], v[180:183], v[28:31]
	v_mfma_f32_16x16x32_bf16 v[24:27], v[140:143], v[180:183], v[24:27]
	v_mfma_f32_16x16x32_bf16 v[12:15], v[132:135], v[188:191], v[12:15]
	v_mfma_f32_16x16x32_bf16 v[8:11], v[140:143], v[188:191], v[8:11]
	s_setprio 0
	s_setprio 1
	v_mfma_f32_16x16x32_bf16 v[52:55], v[144:147], v[160:163], v[52:55]
	v_mfma_f32_16x16x32_bf16 v[48:51], v[152:155], v[160:163], v[48:51]
	v_mfma_f32_16x16x32_bf16 v[36:39], v[144:147], v[168:171], v[36:39]
	v_mfma_f32_16x16x32_bf16 v[32:35], v[152:155], v[168:171], v[32:35]
	v_mfma_f32_16x16x32_bf16 v[20:23], v[144:147], v[176:179], v[20:23]
	v_mfma_f32_16x16x32_bf16 v[16:19], v[152:155], v[176:179], v[16:19]
	v_mfma_f32_16x16x32_bf16 v[4:7], v[144:147], v[184:187], v[4:7]
	v_mfma_f32_16x16x32_bf16 v[0:3], v[152:155], v[184:187], v[0:3]
	v_mfma_f32_16x16x32_bf16 v[52:55], v[148:151], v[164:167], v[52:55]
	v_mfma_f32_16x16x32_bf16 v[48:51], v[156:159], v[164:167], v[48:51]
	v_mfma_f32_16x16x32_bf16 v[36:39], v[148:151], v[172:175], v[36:39]
	v_mfma_f32_16x16x32_bf16 v[32:35], v[156:159], v[172:175], v[32:35]
	v_mfma_f32_16x16x32_bf16 v[20:23], v[148:151], v[180:183], v[20:23]
	v_mfma_f32_16x16x32_bf16 v[16:19], v[156:159], v[180:183], v[16:19]
	v_mfma_f32_16x16x32_bf16 v[4:7], v[148:151], v[188:191], v[4:7]
	v_mfma_f32_16x16x32_bf16 v[0:3], v[156:159], v[188:191], v[0:3]
	s_setprio 0
	s_barrier
	s_add_i32 s89, s89, 2
	s_add_u32 vcc_lo, vcc_lo, 0x100
	s_addc_u32 s88, s88, 0
	s_mov_b64 s[20:21], s[42:43]
	s_cmpk_eq_i32 s89, 0x7c
	s_cbranch_scc1 mk_p6_last
	s_cmpk_gt_u32 s89, 0x7d
	s_cbranch_scc0 .LBB0_883
	s_branch mk_p6_exit
mk_p6_last:
	s_lshl_b32 s98, s75, 8
	s_add_i32 s98, s98, s48
	s_lshl_b32 s98, s98, 12
	s_lshl_b32 s99, s74, 8
	s_or_b32 s99, s99, s50
	s_lshl_b32 s99, s99, 1
	s_add_u32 s98, s98, s99
	s_add_u32 s98, s30, s98
	s_addc_u32 s99, s31, 0
	v_mbcnt_lo_u32_b32 v249, -1, 0
	v_mbcnt_hi_u32_b32 v249, -1, v249
	v_and_b32_e32 v248, 15, v249
	v_lshrrev_b32_e32 v249, 4, v249
	v_lshlrev_b32_e32 v249, 4, v249
	v_lshl_or_b32 v249, v248, 12, v249
	global_load_dwordx4 v[244:247], v249, s[98:99]
	global_load_dwordx4 v[244:247], v249, s[98:99] offset:256
	s_add_u32 s98, s98, 0x10000
	s_addc_u32 s99, s99, 0
	global_load_dwordx4 v[244:247], v249, s[98:99]
	global_load_dwordx4 v[244:247], v249, s[98:99] offset:256
	s_add_u32 s98, s98, 0x10000
	s_addc_u32 s99, s99, 0
	global_load_dwordx4 v[244:247], v249, s[98:99]
	global_load_dwordx4 v[244:247], v249, s[98:99] offset:256
	s_add_u32 s98, s98, 0x10000
	s_addc_u32 s99, s99, 0
	global_load_dwordx4 v[244:247], v249, s[98:99]
	global_load_dwordx4 v[244:247], v249, s[98:99] offset:256
	s_add_u32 s98, s98, 0x50000
	s_addc_u32 s99, s99, 0
	global_load_dwordx4 v[244:247], v249, s[98:99]
	global_load_dwordx4 v[244:247], v249, s[98:99] offset:256
	s_add_u32 s98, s98, 0x10000
	s_addc_u32 s99, s99, 0
	global_load_dwordx4 v[244:247], v249, s[98:99]
	global_load_dwordx4 v[244:247], v249, s[98:99] offset:256
	s_add_u32 s98, s98, 0x10000
	s_addc_u32 s99, s99, 0
	global_load_dwordx4 v[244:247], v249, s[98:99]
	global_load_dwordx4 v[244:247], v249, s[98:99] offset:256
	s_add_u32 s98, s98, 0x10000
	s_addc_u32 s99, s99, 0
	global_load_dwordx4 v[244:247], v249, s[98:99]
	global_load_dwordx4 v[244:247], v249, s[98:99] offset:256
	s_add_u32 s42, s20, 0x100
	s_addc_u32 s43, s21, 0
	s_cmpk_eq_i32 s89, 0x7c
	s_cselect_b32 s28, s86, s42
	s_cselect_b32 s29, s81, s43
	s_cselect_b32 s23, s37, s88
	s_cselect_b32 s22, s87, vcc_lo
	s_add_u32 s26, s28, 0x80
	s_addc_u32 s27, s29, 0
	s_add_u32 s66, s22, 0x80
	s_addc_u32 s67, s23, 0
	s_add_u32 s90, s20, 0x200080
	s_addc_u32 s91, s21, 0
	s_add_u32 s52, s28, 0x200000
	s_addc_u32 s53, s29, 0
	s_add_u32 s56, s22, 0x200000
	s_addc_u32 s57, s23, 0
	s_add_u32 s20, s22, 0x200080
	s_addc_u32 s21, s23, 0
	s_add_i32 s92, 0, 0x10000
	s_add_i32 s93, 0, 0x14000
	v_add_u32_e32 v140, s92, v203
	v_add_u32_e32 v156, s93, v203
	ds_read_b128 v[128:131], v140
	ds_read_b128 v[132:135], v140 offset:1024
	ds_read_b128 v[136:139], v140 offset:2048
	ds_read_b128 v[140:143], v140 offset:3072
	ds_read_b128 v[144:147], v156
	ds_read_b128 v[148:151], v156 offset:1024
	ds_read_b128 v[152:155], v156 offset:2048
	ds_read_b128 v[156:159], v156 offset:3072
	s_add_i32 m0, s73, 0xc000
	ds_read_b128 v[160:163], v205
	ds_read_b128 v[164:167], v205 offset:1024
	ds_read_b128 v[168:171], v205 offset:2048
	ds_read_b128 v[172:175], v205 offset:3072
	ds_read_b128 v[176:179], v205 offset:4096
	ds_read_b128 v[180:183], v205 offset:5120
	ds_read_b128 v[184:187], v205 offset:6144
	ds_read_b128 v[188:191], v205 offset:7168
	global_load_lds_dwordx4 v202, s[90:91]
	s_add_i32 m0, s73, 0xe000
	s_nop 0
	global_load_lds_dwordx4 v204, s[90:91]
	s_waitcnt vmcnt(24)
	s_waitcnt lgkmcnt(0)
	s_barrier
	s_setprio 1
	s_waitcnt lgkmcnt(0)
	v_mfma_f32_16x16x32_bf16 v[124:127], v[128:131], v[160:163], v[124:127]
	v_mfma_f32_16x16x32_bf16 v[120:123], v[136:139], v[160:163], v[120:123]
	v_mfma_f32_16x16x32_bf16 v[108:111], v[128:131], v[168:171], v[108:111]
	v_mfma_f32_16x16x32_bf16 v[104:107], v[136:139], v[168:171], v[104:107]
	v_mfma_f32_16x16x32_bf16 v[92:95], v[128:131], v[176:179], v[92:95]
	v_mfma_f32_16x16x32_bf16 v[88:91], v[136:139], v[176:179], v[88:91]
	v_mfma_f32_16x16x32_bf16 v[76:79], v[128:131], v[184:187], v[76:79]
	v_mfma_f32_16x16x32_bf16 v[72:75], v[136:139], v[184:187], v[72:75]
	v_mfma_f32_16x16x32_bf16 v[124:127], v[132:135], v[164:167], v[124:127]
	v_mfma_f32_16x16x32_bf16 v[120:123], v[140:143], v[164:167], v[120:123]
	v_mfma_f32_16x16x32_bf16 v[108:111], v[132:135], v[172:175], v[108:111]
	v_mfma_f32_16x16x32_bf16 v[104:107], v[140:143], v[172:175], v[104:107]
	v_mfma_f32_16x16x32_bf16 v[92:95], v[132:135], v[180:183], v[92:95]
	v_mfma_f32_16x16x32_bf16 v[88:91], v[140:143], v[180:183], v[88:91]
	v_mfma_f32_16x16x32_bf16 v[76:79], v[132:135], v[188:191], v[76:79]
	v_mfma_f32_16x16x32_bf16 v[72:75], v[140:143], v[188:191], v[72:75]
	s_setprio 0
	s_setprio 1
	v_mfma_f32_16x16x32_bf16 v[116:119], v[144:147], v[160:163], v[116:119]
	v_mfma_f32_16x16x32_bf16 v[112:115], v[152:155], v[160:163], v[112:115]
	v_mfma_f32_16x16x32_bf16 v[100:103], v[144:147], v[168:171], v[100:103]
	v_mfma_f32_16x16x32_bf16 v[96:99], v[152:155], v[168:171], v[96:99]
	v_mfma_f32_16x16x32_bf16 v[84:87], v[144:147], v[176:179], v[84:87]
	v_mfma_f32_16x16x32_bf16 v[80:83], v[152:155], v[176:179], v[80:83]
	v_mfma_f32_16x16x32_bf16 v[68:71], v[144:147], v[184:187], v[68:71]
	v_mfma_f32_16x16x32_bf16 v[64:67], v[152:155], v[184:187], v[64:67]
	v_mfma_f32_16x16x32_bf16 v[116:119], v[148:151], v[164:167], v[116:119]
	v_mfma_f32_16x16x32_bf16 v[112:115], v[156:159], v[164:167], v[112:115]
	v_mfma_f32_16x16x32_bf16 v[100:103], v[148:151], v[172:175], v[100:103]
	v_mfma_f32_16x16x32_bf16 v[96:99], v[156:159], v[172:175], v[96:99]
	v_mfma_f32_16x16x32_bf16 v[84:87], v[148:151], v[180:183], v[84:87]
	v_mfma_f32_16x16x32_bf16 v[80:83], v[156:159], v[180:183], v[80:83]
	v_mfma_f32_16x16x32_bf16 v[68:71], v[148:151], v[188:191], v[68:71]
	v_mfma_f32_16x16x32_bf16 v[64:67], v[156:159], v[188:191], v[64:67]
	s_setprio 0
	s_barrier
	s_add_i32 s90, s92, s33
	s_mov_b32 m0, s90
	ds_read_b128 v[160:163], v205 offset:16384
	ds_read_b128 v[164:167], v205 offset:17408
	ds_read_b128 v[168:171], v205 offset:18432
	ds_read_b128 v[172:175], v205 offset:19456
	ds_read_b128 v[176:179], v205 offset:20480
	ds_read_b128 v[180:183], v205 offset:21504
	ds_read_b128 v[184:187], v205 offset:22528
	ds_read_b128 v[188:191], v205 offset:23552
	global_load_lds_dwordx4 v192, s[22:23]
	s_add_i32 m0, s90, 0x2000
	s_nop 0
	global_load_lds_dwordx4 v206, s[22:23]
	s_add_i32 s22, s93, s33
	s_mov_b32 m0, s22
	s_nop 0
	global_load_lds_dwordx4 v192, s[56:57]
	s_add_i32 m0, s22, 0x2000
	s_nop 0
	global_load_lds_dwordx4 v206, s[56:57]
	s_mov_b32 m0, s73
	s_nop 0
	global_load_lds_dwordx4 v202, s[28:29]
	s_mov_b32 m0, s34
	s_nop 0
	global_load_lds_dwordx4 v204, s[28:29]
	s_waitcnt vmcnt(24)
	s_waitcnt lgkmcnt(0)
	s_barrier
	s_setprio 1
	s_waitcnt lgkmcnt(0)
	v_mfma_f32_16x16x32_bf16 v[60:63], v[128:131], v[160:163], v[60:63]
	v_mfma_f32_16x16x32_bf16 v[56:59], v[136:139], v[160:163], v[56:59]
	v_mfma_f32_16x16x32_bf16 v[44:47], v[128:131], v[168:171], v[44:47]
	v_mfma_f32_16x16x32_bf16 v[40:43], v[136:139], v[168:171], v[40:43]
	v_mfma_f32_16x16x32_bf16 v[28:31], v[128:131], v[176:179], v[28:31]
	v_mfma_f32_16x16x32_bf16 v[24:27], v[136:139], v[176:179], v[24:27]
	v_mfma_f32_16x16x32_bf16 v[12:15], v[128:131], v[184:187], v[12:15]
	v_mfma_f32_16x16x32_bf16 v[8:11], v[136:139], v[184:187], v[8:11]
	v_mfma_f32_16x16x32_bf16 v[60:63], v[132:135], v[164:167], v[60:63]
	v_mfma_f32_16x16x32_bf16 v[56:59], v[140:143], v[164:167], v[56:59]
	v_mfma_f32_16x16x32_bf16 v[44:47], v[132:135], v[172:175], v[44:47]
	v_mfma_f32_16x16x32_bf16 v[40:43], v[140:143], v[172:175], v[40:43]
	v_mfma_f32_16x16x32_bf16 v[28:31], v[132:135], v[180:183], v[28:31]
	v_mfma_f32_16x16x32_bf16 v[24:27], v[140:143], v[180:183], v[24:27]
	v_mfma_f32_16x16x32_bf16 v[12:15], v[132:135], v[188:191], v[12:15]
	v_mfma_f32_16x16x32_bf16 v[8:11], v[140:143], v[188:191], v[8:11]
	s_setprio 0
	s_setprio 1
	v_mfma_f32_16x16x32_bf16 v[52:55], v[144:147], v[160:163], v[52:55]
	v_mfma_f32_16x16x32_bf16 v[48:51], v[152:155], v[160:163], v[48:51]
	v_mfma_f32_16x16x32_bf16 v[36:39], v[144:147], v[168:171], v[36:39]
	v_mfma_f32_16x16x32_bf16 v[32:35], v[152:155], v[168:171], v[32:35]
	v_mfma_f32_16x16x32_bf16 v[20:23], v[144:147], v[176:179], v[20:23]
	v_mfma_f32_16x16x32_bf16 v[16:19], v[152:155], v[176:179], v[16:19]
	v_mfma_f32_16x16x32_bf16 v[4:7], v[144:147], v[184:187], v[4:7]
	v_mfma_f32_16x16x32_bf16 v[0:3], v[152:155], v[184:187], v[0:3]
	v_mfma_f32_16x16x32_bf16 v[52:55], v[148:151], v[164:167], v[52:55]
	v_mfma_f32_16x16x32_bf16 v[48:51], v[156:159], v[164:167], v[48:51]
	v_mfma_f32_16x16x32_bf16 v[36:39], v[148:151], v[172:175], v[36:39]
	v_mfma_f32_16x16x32_bf16 v[32:35], v[156:159], v[172:175], v[32:35]
	v_mfma_f32_16x16x32_bf16 v[20:23], v[148:151], v[180:183], v[20:23]
	v_mfma_f32_16x16x32_bf16 v[16:19], v[156:159], v[180:183], v[16:19]
	v_mfma_f32_16x16x32_bf16 v[4:7], v[148:151], v[188:191], v[4:7]
	v_mfma_f32_16x16x32_bf16 v[0:3], v[156:159], v[188:191], v[0:3]
	s_setprio 0
	s_barrier
; #define PG8_MMA(ai, bj, At, Bt) do { __builtin_amdgcn_s_setprio(1); _Pragma("unroll") for (int m = 0; m < 4; ++m) _Pragma("unroll") for (int n = 0; n < 2; ++n) _Pragma("unroll") for (int k = 0; k < 2; ++k) \
;         acc[ai][bj][m][n] = __builtin_amdgcn_mfma_f32_16x16x32_bf16(Bt[n][k], At[m][k], acc[ai][bj][m][n], 0, 0, 0); __builtin_amdgcn_s_setprio(0); } while (0)
;     ...
;         { const int tmid = (TSW > 0 && TSW < nt) ? TSW : nt;
;           _Pragma("unroll 1") for (int t = 0; t < tmid; t += 2) { PG8_BODY(PG8_MMA) }
	s_add_i32 s22, 0, 0x18000
	s_add_i32 s23, 0, 0x1c000
	v_add_u32_e32 v140, s22, v203
	v_add_u32_e32 v156, s23, v203
	ds_read_b128 v[128:131], v140
	ds_read_b128 v[132:135], v140 offset:1024
	ds_read_b128 v[136:139], v140 offset:2048
	ds_read_b128 v[140:143], v140 offset:3072
	ds_read_b128 v[144:147], v156
	ds_read_b128 v[148:151], v156 offset:1024
	ds_read_b128 v[152:155], v156 offset:2048
	ds_read_b128 v[156:159], v156 offset:3072
	s_mov_b32 m0, s35
	ds_read_b128 v[160:163], v205 offset:32768
	ds_read_b128 v[164:167], v205 offset:33792
	ds_read_b128 v[168:171], v205 offset:34816
	ds_read_b128 v[172:175], v205 offset:35840
	ds_read_b128 v[176:179], v205 offset:36864
	ds_read_b128 v[180:183], v205 offset:37888
	ds_read_b128 v[184:187], v205 offset:38912
	ds_read_b128 v[188:191], v205 offset:39936
	global_load_lds_dwordx4 v202, s[52:53]
	s_mov_b32 m0, s0
	s_nop 0
	global_load_lds_dwordx4 v204, s[52:53]
	s_waitcnt vmcnt(8)
	s_waitcnt lgkmcnt(0)
	s_barrier
	s_setprio 1
	s_waitcnt lgkmcnt(0)
	v_mfma_f32_16x16x32_bf16 v[124:127], v[128:131], v[160:163], v[124:127]
	v_mfma_f32_16x16x32_bf16 v[120:123], v[136:139], v[160:163], v[120:123]
	v_mfma_f32_16x16x32_bf16 v[108:111], v[128:131], v[168:171], v[108:111]
	v_mfma_f32_16x16x32_bf16 v[104:107], v[136:139], v[168:171], v[104:107]
	v_mfma_f32_16x16x32_bf16 v[92:95], v[128:131], v[176:179], v[92:95]
	v_mfma_f32_16x16x32_bf16 v[88:91], v[136:139], v[176:179], v[88:91]
	v_mfma_f32_16x16x32_bf16 v[76:79], v[128:131], v[184:187], v[76:79]
	v_mfma_f32_16x16x32_bf16 v[72:75], v[136:139], v[184:187], v[72:75]
	v_mfma_f32_16x16x32_bf16 v[124:127], v[132:135], v[164:167], v[124:127]
	v_mfma_f32_16x16x32_bf16 v[120:123], v[140:143], v[164:167], v[120:123]
	v_mfma_f32_16x16x32_bf16 v[108:111], v[132:135], v[172:175], v[108:111]
	v_mfma_f32_16x16x32_bf16 v[104:107], v[140:143], v[172:175], v[104:107]
	v_mfma_f32_16x16x32_bf16 v[92:95], v[132:135], v[180:183], v[92:95]
	v_mfma_f32_16x16x32_bf16 v[88:91], v[140:143], v[180:183], v[88:91]
	v_mfma_f32_16x16x32_bf16 v[76:79], v[132:135], v[188:191], v[76:79]
	v_mfma_f32_16x16x32_bf16 v[72:75], v[140:143], v[188:191], v[72:75]
	s_setprio 0
	s_setprio 1
	v_mfma_f32_16x16x32_bf16 v[116:119], v[144:147], v[160:163], v[116:119]
	v_mfma_f32_16x16x32_bf16 v[112:115], v[152:155], v[160:163], v[112:115]
	v_mfma_f32_16x16x32_bf16 v[100:103], v[144:147], v[168:171], v[100:103]
	v_mfma_f32_16x16x32_bf16 v[96:99], v[152:155], v[168:171], v[96:99]
	v_mfma_f32_16x16x32_bf16 v[84:87], v[144:147], v[176:179], v[84:87]
	v_mfma_f32_16x16x32_bf16 v[80:83], v[152:155], v[176:179], v[80:83]
	v_mfma_f32_16x16x32_bf16 v[68:71], v[144:147], v[184:187], v[68:71]
	v_mfma_f32_16x16x32_bf16 v[64:67], v[152:155], v[184:187], v[64:67]
	v_mfma_f32_16x16x32_bf16 v[116:119], v[148:151], v[164:167], v[116:119]
	v_mfma_f32_16x16x32_bf16 v[112:115], v[156:159], v[164:167], v[112:115]
	v_mfma_f32_16x16x32_bf16 v[100:103], v[148:151], v[172:175], v[100:103]
	v_mfma_f32_16x16x32_bf16 v[96:99], v[156:159], v[172:175], v[96:99]
	v_mfma_f32_16x16x32_bf16 v[84:87], v[148:151], v[180:183], v[84:87]
	v_mfma_f32_16x16x32_bf16 v[80:83], v[156:159], v[180:183], v[80:83]
	v_mfma_f32_16x16x32_bf16 v[68:71], v[148:151], v[188:191], v[68:71]
	v_mfma_f32_16x16x32_bf16 v[64:67], v[156:159], v[188:191], v[64:67]
	s_setprio 0
	s_barrier
	s_add_i32 s22, s22, s33
	s_mov_b32 m0, s22
	ds_read_b128 v[160:163], v205 offset:49152
	ds_read_b128 v[164:167], v205 offset:50176
	ds_read_b128 v[168:171], v205 offset:51200
	ds_read_b128 v[172:175], v205 offset:52224
	ds_read_b128 v[176:179], v205 offset:53248
	ds_read_b128 v[180:183], v205 offset:54272
	ds_read_b128 v[184:187], v205 offset:55296
	ds_read_b128 v[188:191], v205 offset:56320
	global_load_lds_dwordx4 v192, s[66:67]
	s_add_i32 m0, s22, 0x2000
	s_add_i32 s22, s23, s33
	global_load_lds_dwordx4 v206, s[66:67]
	s_mov_b32 m0, s22
	s_nop 0
	global_load_lds_dwordx4 v192, s[20:21]
	s_add_i32 m0, s22, 0x2000
	s_nop 0
	global_load_lds_dwordx4 v206, s[20:21]
	s_mov_b32 m0, s1
	s_nop 0
	global_load_lds_dwordx4 v202, s[26:27]
	s_mov_b32 m0, s54
	s_nop 0
	global_load_lds_dwordx4 v204, s[26:27]
	s_waitcnt vmcnt(8)
	s_waitcnt lgkmcnt(0)
	s_barrier
	s_setprio 1
	s_waitcnt lgkmcnt(0)
	v_mfma_f32_16x16x32_bf16 v[60:63], v[128:131], v[160:163], v[60:63]
	v_mfma_f32_16x16x32_bf16 v[56:59], v[136:139], v[160:163], v[56:59]
	v_mfma_f32_16x16x32_bf16 v[44:47], v[128:131], v[168:171], v[44:47]
	v_mfma_f32_16x16x32_bf16 v[40:43], v[136:139], v[168:171], v[40:43]
	v_mfma_f32_16x16x32_bf16 v[28:31], v[128:131], v[176:179], v[28:31]
	v_mfma_f32_16x16x32_bf16 v[24:27], v[136:139], v[176:179], v[24:27]
	v_mfma_f32_16x16x32_bf16 v[12:15], v[128:131], v[184:187], v[12:15]
	v_mfma_f32_16x16x32_bf16 v[8:11], v[136:139], v[184:187], v[8:11]
	v_mfma_f32_16x16x32_bf16 v[60:63], v[132:135], v[164:167], v[60:63]
	v_mfma_f32_16x16x32_bf16 v[56:59], v[140:143], v[164:167], v[56:59]
	v_mfma_f32_16x16x32_bf16 v[44:47], v[132:135], v[172:175], v[44:47]
	v_mfma_f32_16x16x32_bf16 v[40:43], v[140:143], v[172:175], v[40:43]
	v_mfma_f32_16x16x32_bf16 v[28:31], v[132:135], v[180:183], v[28:31]
	v_mfma_f32_16x16x32_bf16 v[24:27], v[140:143], v[180:183], v[24:27]
	v_mfma_f32_16x16x32_bf16 v[12:15], v[132:135], v[188:191], v[12:15]
	v_mfma_f32_16x16x32_bf16 v[8:11], v[140:143], v[188:191], v[8:11]
	s_setprio 0
	s_setprio 1
	v_mfma_f32_16x16x32_bf16 v[52:55], v[144:147], v[160:163], v[52:55]
	v_mfma_f32_16x16x32_bf16 v[48:51], v[152:155], v[160:163], v[48:51]
	v_mfma_f32_16x16x32_bf16 v[36:39], v[144:147], v[168:171], v[36:39]
	v_mfma_f32_16x16x32_bf16 v[32:35], v[152:155], v[168:171], v[32:35]
	v_mfma_f32_16x16x32_bf16 v[20:23], v[144:147], v[176:179], v[20:23]
	v_mfma_f32_16x16x32_bf16 v[16:19], v[152:155], v[176:179], v[16:19]
	v_mfma_f32_16x16x32_bf16 v[4:7], v[144:147], v[184:187], v[4:7]
	v_mfma_f32_16x16x32_bf16 v[0:3], v[152:155], v[184:187], v[0:3]
	v_mfma_f32_16x16x32_bf16 v[52:55], v[148:151], v[164:167], v[52:55]
	v_mfma_f32_16x16x32_bf16 v[48:51], v[156:159], v[164:167], v[48:51]
	v_mfma_f32_16x16x32_bf16 v[36:39], v[148:151], v[172:175], v[36:39]
	v_mfma_f32_16x16x32_bf16 v[32:35], v[156:159], v[172:175], v[32:35]
	v_mfma_f32_16x16x32_bf16 v[20:23], v[148:151], v[180:183], v[20:23]
	v_mfma_f32_16x16x32_bf16 v[16:19], v[156:159], v[180:183], v[16:19]
	v_mfma_f32_16x16x32_bf16 v[4:7], v[148:151], v[188:191], v[4:7]
	v_mfma_f32_16x16x32_bf16 v[0:3], v[156:159], v[188:191], v[0:3]
	s_setprio 0
	s_barrier
	s_add_i32 s89, s89, 2
	s_add_u32 vcc_lo, vcc_lo, 0x100
	s_addc_u32 s88, s88, 0
	s_mov_b64 s[20:21], s[42:43]
mk_p6_exit:
	s_and_b64 vcc, exec, s[82:83]
	s_cbranch_vccz .LBB0_886
	s_barrier
